# attention prompt-unit loop: static s_setprio 1 for waves 0-3 instead (first wave of each SIMD), reset after the loop
# baseline (speedup 1.0000x reference)
.LBB0_543:
	s_andn2_b64 vcc, exec, s[0:1]
	s_cbranch_vccnz .LBB0_589
	s_cmp_eq_u32 s50, 6
	s_cbranch_scc0 .LBB0_589
	s_waitcnt vmcnt(0)
	v_mov_b32_e32 v76, v204
	s_mov_b32 s51, s2
	v_readfirstlane_b32 s0, v76
	s_ashr_i32 s68, s0, 6
	v_readlane_b32 s0, v252, 20
	v_readlane_b32 s1, v252, 21
	s_andn2_b64 vcc, exec, s[0:1]
	s_movk_i32 s0, 0x500
	v_cmp_gt_i32_e64 s[0:1], s0, v76
	v_and_b32_e32 v103, 15, v76
	v_bfe_u32 v136, v76, 4, 2
	v_writelane_b32 v255, s0, 3
	v_lshlrev_b32_e32 v78, 2, v136
	v_or_b32_e32 v0, 0x80, v103
	v_writelane_b32 v255, s1, 4
	s_movk_i32 s0, 0x90
	v_lshlrev_b32_e32 v80, 4, v136
	v_mul_u32_u24_e32 v77, 0x150, v103
	v_mad_u32_u24 v79, v103, s0, 0
	v_sub_u32_e32 v137, v0, v78
	s_cbranch_vccnz .LBB0_566
	s_waitcnt lgkmcnt(0)
	v_min_i32_e32 v3, 0x4ff, v76
	v_ashrrev_i32_e32 v138, 3, v3
	v_readlane_b32 s2, v252, 22
	v_readlane_b32 s0, v252, 29
	s_mov_b32 s8, s0
	v_add_u32_e32 v0, s2, v138
	v_max_i32_e32 v0, 0, v0
	v_add_u32_e32 v0, s8, v0
	v_ashrrev_i32_e32 v1, 31, v0
	v_readlane_b32 s6, v252, 27
	v_lshlrev_b64 v[0:1], 10, v[0:1]
	v_readlane_b32 s7, v252, 28
	s_mov_b32 s3, 0x66666667
	v_mov_b32_e32 v7, v2
	v_lshl_add_u64 v[4:5], s[6:7], 0, v[0:1]
	v_lshlrev_b32_e32 v0, 3, v3
	v_and_b32_e32 v0, 56, v0
	v_lshlrev_b32_e32 v6, 1, v0
	v_mul_hi_i32 v1, v3, s3
	v_lshl_add_u64 v[4:5], v[4:5], 0, v[6:7]
	v_lshrrev_b32_e32 v6, 31, v1
	v_ashrrev_i32_e32 v1, 3, v1
	v_readlane_b32 s1, v252, 30
	v_add_u32_e32 v139, v1, v6
	s_movk_i32 s5, 0xffec
	v_mul_lo_u32 v1, v139, s5
	v_readlane_b32 s0, v252, 23
	v_add_lshl_u32 v140, v1, v3, 3
	v_readlane_b32 s1, v252, 24
	v_add_u32_e32 v1, s2, v140
	s_mov_b32 s4, s0
	v_readlane_b32 s0, v252, 33
	v_max_i32_e32 v1, 0, v1
	v_readlane_b32 s1, v252, 34
	v_add_u32_e32 v3, s4, v139
	v_lshlrev_b32_e32 v8, 1, v1
	v_mov_b64_e32 v[20:21], s[0:1]
	v_min_i32_e32 v1, 0x2ff, v76
	v_mad_i64_i32 v[6:7], s[0:1], v3, s93, v[20:21]
	v_add_u32_e32 v3, 0x200, v1
	v_ashrrev_i32_e32 v141, 3, v3
	v_add_u32_e32 v12, s2, v141
	v_max_i32_e32 v12, 0, v12
	v_add_u32_e32 v12, s8, v12
	v_ashrrev_i32_e32 v13, 31, v12
	v_lshlrev_b32_e32 v1, 3, v1
	v_lshlrev_b64 v[12:13], 10, v[12:13]
	v_and_b32_e32 v28, 56, v1
	v_lshl_add_u64 v[12:13], s[6:7], 0, v[12:13]
	v_lshlrev_b32_e32 v14, 1, v28
	v_mov_b32_e32 v15, v2
	v_mul_hi_i32 v1, v3, s3
	v_lshl_add_u64 v[12:13], v[12:13], 0, v[14:15]
	v_lshrrev_b32_e32 v14, 31, v1
	v_ashrrev_i32_e32 v1, 3, v1
	v_add_u32_e32 v142, v1, v14
	v_mul_lo_u32 v1, v142, s5
	v_add_lshl_u32 v143, v1, v3, 3
	v_add_u32_e32 v1, s2, v143
	v_max_i32_e32 v1, 0, v1
	v_add_u32_e32 v3, s4, v142
	v_lshlrev_b32_e32 v16, 1, v1
	v_min_i32_e32 v1, 0xff, v76
	v_mad_i64_i32 v[14:15], s[0:1], v3, s93, v[20:21]
	v_add_u32_e32 v3, 0x400, v1
	v_ashrrev_i32_e32 v144, 3, v3
	v_add_u32_e32 v22, s2, v144
	v_max_i32_e32 v22, 0, v22
	v_add_u32_e32 v22, s8, v22
	v_ashrrev_i32_e32 v23, 31, v22
	v_lshlrev_b32_e32 v1, 3, v1
	v_lshlrev_b64 v[22:23], 10, v[22:23]
	v_and_b32_e32 v30, 56, v1
	v_lshl_add_u64 v[22:23], s[6:7], 0, v[22:23]
	v_lshlrev_b32_e32 v24, 1, v30
	v_mov_b32_e32 v25, v2
	v_mul_hi_i32 v1, v3, s3
	v_lshl_add_u64 v[22:23], v[22:23], 0, v[24:25]
	v_lshrrev_b32_e32 v24, 31, v1
	v_ashrrev_i32_e32 v1, 3, v1
	v_add_u32_e32 v145, v1, v24
	v_mul_lo_u32 v1, v145, s5
	v_add_lshl_u32 v146, v1, v3, 3
	v_add_u32_e32 v1, s2, v146
	v_max_i32_e32 v1, 0, v1
	v_add_u32_e32 v3, s4, v145
	v_mov_b32_e32 v9, v2
	v_mov_b32_e32 v17, v2
	v_mad_i64_i32 v[20:21], s[0:1], v3, s93, v[20:21]
	v_lshlrev_b32_e32 v24, 1, v1
	v_lshl_add_u64 v[8:9], v[6:7], 0, v[8:9]
	v_lshl_add_u64 v[16:17], v[14:15], 0, v[16:17]
	v_lshl_add_u64 v[24:25], v[20:21], 0, v[24:25]
	global_load_dwordx4 v[4:7], v[4:5], off
	s_nop 0
	global_load_dwordx4 v[8:11], v[8:9], off
	s_nop 0
	global_load_dwordx4 v[12:15], v[12:13], off
	s_nop 0
	global_load_dwordx4 v[16:19], v[16:17], off
	s_nop 0
	global_load_dwordx4 v[20:23], v[22:23], off
	s_nop 0
	global_load_dwordx4 v[24:27], v[24:25], off
	v_mul_hi_i32 v29, v76, s3
	v_readlane_b32 s0, v251, 22
	v_lshrrev_b32_e32 v31, 31, v29
	v_ashrrev_i32_e32 v29, 3, v29
	v_lshlrev_b32_e32 v32, 3, v136
	v_mov_b32_e32 v33, v2
	v_readlane_b32 s1, v251, 23
	v_add_u32_e32 v29, v29, v31
	s_movk_i32 s4, 0x150
	v_lshl_add_u64 v[84:85], s[0:1], 0, v[32:33]
	v_mad_u64_u32 v[34:35], s[0:1], v29, s5, v[76:77]
	v_lshlrev_b32_e32 v147, 3, v34
	v_lshlrev_b32_e32 v31, 4, v34
	v_add_u32_e32 v34, 0x200, v76
	s_movk_i32 s0, 0x300
	v_mul_hi_i32 v35, v34, s3
	v_cmp_gt_i32_e64 s[0:1], s0, v76
	v_lshrrev_b32_e32 v37, 31, v35
	v_ashrrev_i32_e32 v35, 3, v35
	v_writelane_b32 v255, s0, 5
	v_add_u32_e32 v37, v35, v37
	v_ashrrev_i32_e32 v148, 3, v34
	v_writelane_b32 v255, s1, 6
	v_mad_u64_u32 v[34:35], s[0:1], v37, s5, v[34:35]
	v_lshlrev_b32_e32 v149, 3, v34
	v_mul_lo_u32 v35, v37, s4
	v_lshlrev_b32_e32 v38, 4, v34
	v_add_u32_e32 v34, 0x400, v76
	v_add_u32_e32 v37, 0, v35
	s_movk_i32 s0, 0x100
	v_mul_hi_i32 v35, v34, s3
	v_cmp_gt_i32_e64 s[0:1], s0, v76
	v_lshrrev_b32_e32 v40, 31, v35
	v_ashrrev_i32_e32 v35, 3, v35
	v_writelane_b32 v255, s0, 7
	v_add_u32_e32 v40, v35, v40
	v_ashrrev_i32_e32 v150, 3, v34
	v_writelane_b32 v255, s1, 8
	v_mad_u64_u32 v[34:35], s[0:1], v40, s5, v[34:35]
	v_readlane_b32 s0, v255, 1
	v_readlane_b32 s1, v255, 2
	s_lshl_b32 s0, s0, 6
	v_writelane_b32 v255, s0, 9
	v_readlane_b32 s0, v253, 53
	v_readlane_b32 s1, v253, 54
	v_mul_lo_u32 v29, v29, s4
	v_mul_lo_u32 v35, v40, s4
	v_lshl_add_u64 v[86:87], s[0:1], 0, v[32:33]
	s_movk_i32 s1, 0x80
	v_cmp_gt_u32_e64 s[4:5], s1, v137
	s_movk_i32 s0, 0x81
	v_add_u32_e32 v33, -3, v137
	v_writelane_b32 v255, s4, 10
	v_add_u32_e32 v40, 0, v32
	v_add_u32_e32 v32, -2, v137
	v_writelane_b32 v255, s5, 11
	v_cmp_gt_u32_e64 s[4:5], s0, v137
	s_movk_i32 s0, 0x7f
	v_or_b32_e32 v42, 0x90, v103
	v_writelane_b32 v255, s4, 12
	v_mov_b32_e32 v81, v2
	v_sub_u32_e32 v42, v42, v78
	v_writelane_b32 v255, s5, 13
	v_cmp_gt_u32_e64 s[4:5], s1, v33
	v_add_u32_e32 v33, 0xffffff7e, v137
	v_lshl_add_u64 v[82:83], s[64:65], 0, v[80:81]
	v_writelane_b32 v255, s4, 14
	v_ashrrev_i32_e32 v81, 3, v76
	s_movk_i32 s2, 0x90
	v_writelane_b32 v255, s5, 15
	v_cmp_gt_u32_e64 s[4:5], s1, v32
	v_add_u32_e32 v32, 0xffffff7f, v137
	v_or_b32_e32 v153, 16, v103
	v_writelane_b32 v255, s4, 16
	v_subrev_u32_e32 v44, 17, v42
	v_mul_lo_u32 v3, v81, s2
	v_writelane_b32 v255, s5, 17
	v_cmp_lt_u32_e64 s[4:5], s0, v137
	v_mul_lo_u32 v36, v148, s2
	v_mul_lo_u32 v39, v150, s2
	v_writelane_b32 v255, s4, 18
	v_mad_u32_u24 v154, v153, s2, 0
	v_cmp_gt_u32_e64 s[2:3], s1, v44
	v_writelane_b32 v255, s5, 19
	v_cmp_gt_u32_e64 s[4:5], s1, v33
	v_add_u32_e32 v43, -16, v42
	v_subrev_u32_e32 v44, 19, v42
	v_writelane_b32 v255, s4, 20
	v_lshlrev_b32_e32 v1, 4, v76
	v_cvt_f32_ubyte0_e32 v155, v42
	v_writelane_b32 v255, s5, 21
	v_cmp_gt_u32_e64 s[4:5], s1, v32
	v_add_u32_e32 v32, 0xffffff7d, v137
	v_and_b32_e32 v1, 0x70, v1
	v_writelane_b32 v255, s4, 22
	v_add_u32_e32 v1, 0, v1
	v_add_u32_e32 v29, 0, v29
	v_writelane_b32 v255, s5, 23
	v_cmp_gt_u32_e64 s[4:5], s1, v32
	v_lshlrev_b32_e32 v151, 3, v34
	v_add_u32_e32 v35, 0, v35
	v_writelane_b32 v255, s4, 24
	v_lshlrev_b32_e32 v34, 4, v34
	v_add_u32_e32 v32, 0x900, v154
	v_writelane_b32 v255, s5, 25
	v_writelane_b32 v255, s2, 26
	v_add_u32_e32 v33, 0x1200, v154
	v_add_u32_e32 v41, 0x3f00, v154
	v_writelane_b32 v255, s3, 27
	v_cmp_gt_u32_e64 s[2:3], s1, v43
	v_subrev_u32_e32 v43, 18, v42
	v_cvt_f32_ubyte0_e32 v152, v137
	v_writelane_b32 v255, s2, 28
	v_add_u32_e32 v156, v1, v3
	v_add_u32_e32 v157, v29, v31
	v_writelane_b32 v255, s3, 29
	v_cmp_gt_u32_e64 s[2:3], s1, v44
	v_add_u32_e32 v44, 0xffffff6f, v42
	v_add_u32_e32 v158, v1, v36
	v_writelane_b32 v255, s2, 30
	v_add_u32_e32 v159, v37, v38
	v_add_u32_e32 v161, v1, v39
	v_writelane_b32 v255, s3, 31
	v_cmp_gt_u32_e64 s[2:3], s1, v43
	v_add_u32_e32 v43, 0xffffff70, v42
	v_add_u32_e32 v166, v35, v34
	v_writelane_b32 v255, s2, 32
	v_lshlrev_b32_e32 v88, 1, v0
	v_lshlrev_b32_e32 v90, 1, v28
	v_writelane_b32 v255, s3, 33
	v_cmp_gt_u32_e64 s[2:3], s1, v44
	v_lshlrev_b32_e32 v92, 1, v30
	v_add_u32_e32 v167, v32, v80
	v_writelane_b32 v255, s2, 34
	v_add_u32_e32 v168, v33, v80
	v_add_u32_e32 v169, v41, v80
	v_writelane_b32 v255, s3, 35
	v_cmp_gt_u32_e64 s[2:3], s1, v43
	v_add_u32_e32 v43, 0xffffff6e, v42
	v_add_u32_e32 v42, 0xffffff6d, v42
	v_writelane_b32 v255, s2, 36
	v_add_u32_e32 v170, v79, v80
	v_add_u32_e32 v171, v40, v77
	v_writelane_b32 v255, s3, 37
	v_cmp_gt_u32_e64 s[2:3], s1, v43
	v_cmp_gt_u32_e64 s[0:1], s1, v42
	s_mov_b32 s6, s51
	v_writelane_b32 v255, s2, 38
	s_nop 1
	v_writelane_b32 v255, s3, 39
	v_writelane_b32 v255, s0, 40
	s_nop 1
	v_writelane_b32 v255, s1, 41
	s_cmp_ge_u32 s68, 4
	s_cbranch_scc1 .Lattn_prio_skip
	s_setprio 1
